# attention loops: the serial K-fragment re-reads of the Q*K section are also hoisted (v238..v249) and batched behind counted waits
# baseline (speedup 1.0000x reference)
.LBB0_1035:
	s_add_i32 s12, s13, 1
	s_bitcmp1_b32 s13, 0
	s_cselect_b32 s13, 0x4800, 0
	v_or_b32_e32 v80, s13, v42
	v_add_u32_e32 v55, v80, v47
	ds_read_b128 v[56:59], v55
	ds_read_b128 v[60:63], v55 offset:64
	v_add_u32_e32 v84, v80, v53
	ds_read_b128 v[80:83], v84 offset:9216
	s_andn2_b64 vcc, exec, s[66:67]
	s_waitcnt lgkmcnt(2)
	v_mfma_f32_16x16x32_bf16 v[56:59], v[56:59], v[2:5], 0
	ds_read_b128 v[64:67], v55 offset:640
	ds_read_b128 v[68:71], v55 offset:4672
	ds_read_b128 v[72:75], v55 offset:5248
	s_waitcnt lgkmcnt(4)
	ds_read_b128 v[238:241], v55 offset:576
	ds_read_b128 v[242:245], v55 offset:4608
	ds_read_b128 v[246:249], v55 offset:5184
	v_mfma_f32_16x16x32_bf16 v[56:59], v[60:63], v[6:9], v[56:59]
	s_waitcnt lgkmcnt(2)
	v_mfma_f32_16x16x32_bf16 v[60:63], v[238:241], v[2:5], 0
	v_mfma_f32_16x16x32_bf16 v[60:63], v[64:67], v[6:9], v[60:63]
	s_waitcnt lgkmcnt(1)
	v_mfma_f32_16x16x32_bf16 v[64:67], v[242:245], v[2:5], 0
	v_mfma_f32_16x16x32_bf16 v[64:67], v[68:71], v[6:9], v[64:67]
	v_mul_f32_e32 v55, 0x3e38aa3b, v56
	s_waitcnt lgkmcnt(0)
	v_mfma_f32_16x16x32_bf16 v[68:71], v[246:249], v[2:5], 0
	v_mfma_f32_16x16x32_bf16 v[68:71], v[72:75], v[6:9], v[68:71]
	v_mul_f32_e32 v72, 0x3e38aa3b, v57
	v_max3_f32 v55, v55, s88, v72
	v_mul_f32_e32 v72, 0x3e38aa3b, v58
	v_mul_f32_e32 v73, 0x3e38aa3b, v59
	v_max3_f32 v55, v55, v72, v73
	v_mul_f32_e32 v72, 0x3e38aa3b, v60
	v_mul_f32_e32 v73, 0x3e38aa3b, v61
	v_max3_f32 v55, v55, v72, v73
	v_mul_f32_e32 v72, 0x3e38aa3b, v62
	v_mul_f32_e32 v73, 0x3e38aa3b, v63
	v_max3_f32 v55, v55, v72, v73
	v_mul_f32_e32 v72, 0x3e38aa3b, v64
	v_mul_f32_e32 v73, 0x3e38aa3b, v65
	v_max3_f32 v55, v55, v72, v73
	v_mul_f32_e32 v72, 0x3e38aa3b, v66
	v_mul_f32_e32 v73, 0x3e38aa3b, v67
	v_max3_f32 v55, v55, v72, v73
	v_mul_f32_e32 v72, 0x3e38aa3b, v68
	v_mul_f32_e32 v73, 0x3e38aa3b, v69
	v_max3_f32 v55, v55, v72, v73
	v_mul_f32_e32 v72, 0x3e38aa3b, v70
	v_mul_f32_e32 v73, 0x3e38aa3b, v71
	v_max3_f32 v55, v55, v72, v73
	ds_bpermute_b32 v72, v43, v55
	s_waitcnt lgkmcnt(0)
	v_max_f32_e32 v72, v72, v72
	v_max_f32_e32 v55, v55, v72
	ds_bpermute_b32 v72, v1, v55
	s_waitcnt lgkmcnt(0)
	ds_read_b128 v[210:213], v84 offset:11520
	ds_read_b128 v[214:217], v84 offset:11584
	ds_read_b128 v[218:221], v84 offset:13824
	ds_read_b128 v[222:225], v84 offset:13888
	ds_read_b128 v[226:229], v84 offset:16128
	ds_read_b128 v[230:233], v84 offset:16192
	v_max3_f32 v55, v52, v55, v72
	v_sub_f32_e32 v52, v52, v55
	v_fma_f32 v56, v56, s91, -v55
	v_fma_f32 v57, v57, s91, -v55
	v_fma_f32 v58, v58, s91, -v55
	v_fma_f32 v59, v59, s91, -v55
	v_fma_f32 v60, v60, s91, -v55
	v_fma_f32 v61, v61, s91, -v55
	v_fma_f32 v62, v62, s91, -v55
	v_fma_f32 v63, v63, s91, -v55
	v_exp_f32_e32 v52, v52
	v_exp_f32_e32 v56, v56
	v_exp_f32_e32 v57, v57
	v_exp_f32_e32 v58, v58
	v_exp_f32_e32 v59, v59
	v_exp_f32_e32 v60, v60
	v_exp_f32_e32 v61, v61
	v_exp_f32_e32 v62, v62
	v_exp_f32_e32 v63, v63
	v_pk_mul_f32 v[28:29], v[28:29], v[52:53] op_sel_hi:[1,0]
	v_pk_mul_f32 v[26:27], v[26:27], v[52:53] op_sel_hi:[1,0]
	v_cvt_pk_bf16_f32 v72, v56, v57
	v_cvt_pk_bf16_f32 v73, v58, v59
	v_cvt_pk_bf16_f32 v74, v60, v61
	v_cvt_pk_bf16_f32 v75, v62, v63
	v_fma_f32 v64, v64, s91, -v55
	v_fma_f32 v65, v65, s91, -v55
	v_mfma_f32_16x16x32_bf16 v[26:29], v[80:83], v[72:75], v[26:29]
	ds_read_b128 v[80:83], v84 offset:9280
	v_fma_f32 v66, v66, s91, -v55
	v_fma_f32 v67, v67, s91, -v55
	v_fma_f32 v68, v68, s91, -v55
	v_fma_f32 v69, v69, s91, -v55
	v_fma_f32 v70, v70, s91, -v55
	v_fma_f32 v71, v71, s91, -v55
	v_exp_f32_e32 v64, v64
	v_exp_f32_e32 v65, v65
	v_exp_f32_e32 v66, v66
	v_exp_f32_e32 v67, v67
	v_exp_f32_e32 v68, v68
	v_exp_f32_e32 v69, v69
	v_exp_f32_e32 v70, v70
	v_exp_f32_e32 v71, v71
	v_cvt_pk_bf16_f32 v76, v64, v65
	v_cvt_pk_bf16_f32 v77, v66, v67
	v_cvt_pk_bf16_f32 v78, v68, v69
	v_cvt_pk_bf16_f32 v79, v70, v71
	v_pk_mul_f32 v[32:33], v[32:33], v[52:53] op_sel_hi:[1,0]
	v_pk_mul_f32 v[30:31], v[30:31], v[52:53] op_sel_hi:[1,0]
	s_waitcnt lgkmcnt(0)
	v_mfma_f32_16x16x32_bf16 v[26:29], v[80:83], v[76:79], v[26:29]
	v_pk_mul_f32 v[36:37], v[36:37], v[52:53] op_sel_hi:[1,0]
	v_pk_mul_f32 v[34:35], v[34:35], v[52:53] op_sel_hi:[1,0]
	s_waitcnt lgkmcnt(6)
	v_mfma_f32_16x16x32_bf16 v[30:33], v[210:213], v[72:75], v[30:33]
	v_pk_mul_f32 v[40:41], v[40:41], v[52:53] op_sel_hi:[1,0]
	v_pk_mul_f32 v[38:39], v[38:39], v[52:53] op_sel_hi:[1,0]
	s_waitcnt lgkmcnt(5)
	v_mfma_f32_16x16x32_bf16 v[30:33], v[214:217], v[76:79], v[30:33]
	s_waitcnt lgkmcnt(4)
	v_mfma_f32_16x16x32_bf16 v[34:37], v[218:221], v[72:75], v[34:37]
	s_waitcnt lgkmcnt(3)
	v_mfma_f32_16x16x32_bf16 v[34:37], v[222:225], v[76:79], v[34:37]
	s_waitcnt lgkmcnt(2)
	v_mfma_f32_16x16x32_bf16 v[38:41], v[226:229], v[72:75], v[38:41]
	s_waitcnt lgkmcnt(1)
	v_mfma_f32_16x16x32_bf16 v[38:41], v[230:233], v[76:79], v[38:41]
	s_cbranch_vccnz .LBB0_1037
	s_bitcmp1_b32 s12, 0
	s_cselect_b32 s13, 0x4800, 0
	v_add_u32_e32 v72, s13, v46
	s_waitcnt vmcnt(3)
	ds_write_b128 v72, v[14:17]
	s_waitcnt vmcnt(2)
	ds_write_b128 v72, v[10:13] offset:16
	s_waitcnt vmcnt(0)
	ds_write_b128 v72, v[22:25] offset:9216
	ds_write_b128 v72, v[18:21] offset:9232

.LBB0_1056:
	s_cmp_gt_u32 s14, 3
	s_cselect_b64 s[68:69], -1, 0
	s_bitcmp1_b32 s14, 0
	s_cselect_b32 s14, 0x4800, 0
	v_or_b32_e32 v87, s14, v58
	v_add_u32_e32 v61, v87, v56
	ds_read_b128 v[62:65], v61
	ds_read_b128 v[66:69], v61 offset:64
	v_add_u32_e32 v87, v87, v57
	ds_read_b128 v[88:91], v87 offset:9216
	s_waitcnt vmcnt(1) lgkmcnt(2)
	v_mfma_f32_16x16x32_bf16 v[62:65], v[62:65], v[2:5], 0
	ds_read_b128 v[70:73], v61 offset:640
	ds_read_b128 v[74:77], v61 offset:4672
	ds_read_b128 v[78:81], v61 offset:5248
	s_waitcnt vmcnt(0) lgkmcnt(4)
	ds_read_b128 v[238:241], v61 offset:576
	ds_read_b128 v[242:245], v61 offset:4608
	ds_read_b128 v[246:249], v61 offset:5184
	v_mfma_f32_16x16x32_bf16 v[62:65], v[66:69], v[6:9], v[62:65]
	s_waitcnt lgkmcnt(2)
	v_mfma_f32_16x16x32_bf16 v[66:69], v[238:241], v[2:5], 0
	s_nop 4
	v_mul_f32_e32 v62, 0x3e38aa3b, v62
	v_mul_f32_e32 v63, 0x3e38aa3b, v63
	v_mul_f32_e32 v64, 0x3e38aa3b, v64
	v_mfma_f32_16x16x32_bf16 v[66:69], v[70:73], v[6:9], v[66:69]
	v_mul_f32_e32 v65, 0x3e38aa3b, v65
	s_waitcnt lgkmcnt(1)
	v_mfma_f32_16x16x32_bf16 v[70:73], v[242:245], v[2:5], 0
	s_nop 3
	v_mul_f32_e32 v66, 0x3e38aa3b, v66
	v_mul_f32_e32 v67, 0x3e38aa3b, v67
	v_mul_f32_e32 v68, 0x3e38aa3b, v68
	v_mfma_f32_16x16x32_bf16 v[70:73], v[74:77], v[6:9], v[70:73]
	v_add_u32_e32 v61, s12, v59
	v_mul_f32_e32 v69, 0x3e38aa3b, v69
	s_waitcnt lgkmcnt(0)
	v_mfma_f32_16x16x32_bf16 v[74:77], v[246:249], v[2:5], 0
	s_nop 2
	v_mul_f32_e32 v70, 0x3e38aa3b, v70
	v_mul_f32_e32 v71, 0x3e38aa3b, v71
	v_mul_f32_e32 v72, 0x3e38aa3b, v72
	v_mfma_f32_16x16x32_bf16 v[74:77], v[78:81], v[6:9], v[74:77]
	v_add_u32_e32 v78, 0xfffffe3f, v61
	v_cmp_gt_u32_e32 vcc, s36, v78
	s_and_b64 vcc, s[68:69], vcc
	v_add_u32_e32 v78, 0xfffffe40, v61
	v_cndmask_b32_e32 v62, v62, v150, vcc
	v_cmp_gt_u32_e32 vcc, s36, v78
	s_and_b64 vcc, s[68:69], vcc
	v_add_u32_e32 v79, 0xfffffe41, v61
	v_cndmask_b32_e32 v63, v63, v150, vcc
	v_cmp_gt_u32_e32 vcc, s36, v79
	s_and_b64 vcc, s[68:69], vcc
	v_add_u32_e32 v79, 0xfffffe42, v61
	v_cndmask_b32_e32 v64, v64, v150, vcc
	v_cmp_gt_u32_e32 vcc, s36, v79
	s_and_b64 vcc, s[68:69], vcc
	v_add_u32_e32 v79, 0xfffffe43, v61
	v_cndmask_b32_e32 v65, v65, v150, vcc
	v_cmp_gt_u32_e32 vcc, s36, v79
	s_and_b64 vcc, s[68:69], vcc
	v_add_u32_e32 v79, 0xfffffe44, v61
	v_cndmask_b32_e32 v66, v66, v150, vcc
	v_cmp_gt_u32_e32 vcc, s36, v79
	s_and_b64 vcc, s[68:69], vcc
	v_add_u32_e32 v79, 0xfffffe45, v61
	v_cndmask_b32_e32 v67, v67, v150, vcc
	v_cmp_gt_u32_e32 vcc, s36, v79
	s_and_b64 vcc, s[68:69], vcc
	v_add_u32_e32 v79, 0xfffffe46, v61
	v_cndmask_b32_e32 v68, v68, v150, vcc
	v_cmp_gt_u32_e32 vcc, s36, v79
	s_and_b64 vcc, s[68:69], vcc
	v_add_u32_e32 v79, 0xfffffe5f, v61
	v_cndmask_b32_e32 v69, v69, v150, vcc
	v_cmp_gt_u32_e32 vcc, s36, v79
	s_and_b64 vcc, s[68:69], vcc
	v_add_u32_e32 v79, 0xfffffe60, v61
	v_cndmask_b32_e32 v70, v70, v150, vcc
	v_cmp_gt_u32_e32 vcc, s36, v79
	s_and_b64 vcc, s[68:69], vcc
	v_add_u32_e32 v79, 0xfffffe61, v61
	v_cndmask_b32_e32 v71, v71, v150, vcc
	v_cmp_gt_u32_e32 vcc, s36, v79
	s_and_b64 vcc, s[68:69], vcc
	v_add_u32_e32 v79, 0xfffffe62, v61
	v_cndmask_b32_e32 v72, v72, v150, vcc
	v_cmp_gt_u32_e32 vcc, s36, v79
	v_mul_f32_e32 v73, 0x3e38aa3b, v73
	s_and_b64 vcc, s[68:69], vcc
	v_add_u32_e32 v79, 0xfffffe63, v61
	v_cndmask_b32_e32 v73, v73, v150, vcc
	v_cmp_gt_u32_e32 vcc, s36, v79
	v_mul_f32_e32 v74, 0x3e38aa3b, v74
	s_and_b64 vcc, s[68:69], vcc
	v_add_u32_e32 v79, 0xfffffe64, v61
	v_max3_f32 v78, v62, s88, v63
	v_cndmask_b32_e32 v74, v74, v150, vcc
	v_cmp_gt_u32_e32 vcc, s36, v79
	v_max3_f32 v78, v78, v64, v65
	v_mul_f32_e32 v75, 0x3e38aa3b, v75
	s_and_b64 vcc, s[68:69], vcc
	v_add_u32_e32 v79, 0xfffffe65, v61
	v_max3_f32 v78, v78, v66, v67
	v_cndmask_b32_e32 v75, v75, v150, vcc
	v_cmp_gt_u32_e32 vcc, s36, v79
	v_max3_f32 v78, v78, v68, v69
	v_mul_f32_e32 v76, 0x3e38aa3b, v76
	s_and_b64 vcc, s[68:69], vcc
	v_add_u32_e32 v61, 0xfffffe66, v61
	v_max3_f32 v78, v78, v70, v71
	v_cndmask_b32_e32 v76, v76, v150, vcc
	v_cmp_gt_u32_e32 vcc, s36, v61
	v_max3_f32 v78, v78, v72, v73
	v_mul_f32_e32 v77, 0x3e38aa3b, v77
	s_and_b64 vcc, s[68:69], vcc
	v_max3_f32 v78, v78, v74, v75
	v_cndmask_b32_e32 v77, v77, v150, vcc
	v_max3_f32 v61, v78, v76, v77
	ds_bpermute_b32 v78, v45, v61
	s_andn2_b64 vcc, exec, s[66:67]
	s_waitcnt lgkmcnt(0)
	v_max_f32_e32 v78, v78, v78
	v_max_f32_e32 v61, v61, v78
	ds_bpermute_b32 v78, v55, v61
	s_waitcnt lgkmcnt(0)
	ds_read_b128 v[210:213], v87 offset:11520
	ds_read_b128 v[214:217], v87 offset:11584
	ds_read_b128 v[218:221], v87 offset:13824
	ds_read_b128 v[222:225], v87 offset:13888
	ds_read_b128 v[226:229], v87 offset:16128
	ds_read_b128 v[230:233], v87 offset:16192
	v_max3_f32 v61, v52, v61, v78
	v_sub_f32_e32 v52, v52, v61
	v_sub_f32_e32 v62, v62, v61
	v_sub_f32_e32 v63, v63, v61
	v_sub_f32_e32 v64, v64, v61
	v_sub_f32_e32 v65, v65, v61
	v_sub_f32_e32 v66, v66, v61
	v_sub_f32_e32 v67, v67, v61
	v_sub_f32_e32 v68, v68, v61
	v_sub_f32_e32 v69, v69, v61
	v_exp_f32_e32 v52, v52
	v_exp_f32_e32 v62, v62
	v_exp_f32_e32 v63, v63
	v_exp_f32_e32 v64, v64
	v_exp_f32_e32 v65, v65
	v_exp_f32_e32 v66, v66
	v_exp_f32_e32 v67, v67
	v_exp_f32_e32 v68, v68
	v_exp_f32_e32 v69, v69
	v_pk_mul_f32 v[28:29], v[28:29], v[52:53] op_sel_hi:[1,0]
	v_pk_mul_f32 v[26:27], v[26:27], v[52:53] op_sel_hi:[1,0]
	v_cvt_pk_bf16_f32 v78, v62, v63
	v_cvt_pk_bf16_f32 v79, v64, v65
	v_cvt_pk_bf16_f32 v80, v66, v67
	v_cvt_pk_bf16_f32 v81, v68, v69
	v_sub_f32_e32 v70, v70, v61
	v_sub_f32_e32 v71, v71, v61
	v_mfma_f32_16x16x32_bf16 v[26:29], v[88:91], v[78:81], v[26:29]
	ds_read_b128 v[88:91], v87 offset:9280
	v_sub_f32_e32 v72, v72, v61
	v_sub_f32_e32 v73, v73, v61
	v_sub_f32_e32 v74, v74, v61
	v_sub_f32_e32 v75, v75, v61
	v_sub_f32_e32 v76, v76, v61
	v_sub_f32_e32 v77, v77, v61
	v_exp_f32_e32 v70, v70
	v_exp_f32_e32 v71, v71
	v_exp_f32_e32 v72, v72
	v_exp_f32_e32 v73, v73
	v_exp_f32_e32 v74, v74
	v_exp_f32_e32 v75, v75
	v_exp_f32_e32 v76, v76
	v_exp_f32_e32 v77, v77
	v_cvt_pk_bf16_f32 v82, v70, v71
	v_cvt_pk_bf16_f32 v83, v72, v73
	v_cvt_pk_bf16_f32 v84, v74, v75
	v_cvt_pk_bf16_f32 v85, v76, v77
	v_pk_mul_f32 v[32:33], v[32:33], v[52:53] op_sel_hi:[1,0]
	v_pk_mul_f32 v[30:31], v[30:31], v[52:53] op_sel_hi:[1,0]
	s_waitcnt lgkmcnt(0)
	v_mfma_f32_16x16x32_bf16 v[26:29], v[88:91], v[82:85], v[26:29]
	v_pk_mul_f32 v[36:37], v[36:37], v[52:53] op_sel_hi:[1,0]
	v_pk_mul_f32 v[34:35], v[34:35], v[52:53] op_sel_hi:[1,0]
	s_waitcnt lgkmcnt(6)
	v_mfma_f32_16x16x32_bf16 v[30:33], v[210:213], v[78:81], v[30:33]
	v_pk_mul_f32 v[40:41], v[40:41], v[52:53] op_sel_hi:[1,0]
	v_pk_mul_f32 v[38:39], v[38:39], v[52:53] op_sel_hi:[1,0]
	s_waitcnt lgkmcnt(5)
	v_mfma_f32_16x16x32_bf16 v[30:33], v[214:217], v[82:85], v[30:33]
	s_waitcnt lgkmcnt(4)
	v_mfma_f32_16x16x32_bf16 v[34:37], v[218:221], v[78:81], v[34:37]
	s_waitcnt lgkmcnt(3)
	v_mfma_f32_16x16x32_bf16 v[34:37], v[222:225], v[82:85], v[34:37]
	s_waitcnt lgkmcnt(2)
	v_mfma_f32_16x16x32_bf16 v[38:41], v[226:229], v[78:81], v[38:41]
	s_waitcnt lgkmcnt(1)
	v_mfma_f32_16x16x32_bf16 v[38:41], v[230:233], v[82:85], v[38:41]
	s_cbranch_vccnz .LBB0_1058
	s_bitcmp1_b32 s13, 0
	s_cselect_b32 s14, 0x4800, 0
	v_add_u32_e32 v78, s14, v48
	ds_write_b128 v78, v[14:17]
	ds_write_b128 v78, v[10:13] offset:16
	ds_write_b128 v78, v[22:25] offset:9216
	ds_write_b128 v78, v[18:21] offset:9232

.LBB0_1163:
	s_add_i32 s12, s13, 1
	s_bitcmp1_b32 s13, 0
	s_cselect_b32 s13, 0x4800, 0
	v_or_b32_e32 v80, s13, v42
	v_add_u32_e32 v55, v80, v47
	ds_read_b128 v[56:59], v55
	ds_read_b128 v[60:63], v55 offset:64
	v_add_u32_e32 v84, v80, v53
	ds_read_b128 v[80:83], v84 offset:9216
	s_andn2_b64 vcc, exec, s[60:61]
	s_waitcnt lgkmcnt(2)
	v_mfma_f32_16x16x32_bf16 v[56:59], v[56:59], v[2:5], 0
	ds_read_b128 v[64:67], v55 offset:640
	ds_read_b128 v[68:71], v55 offset:4672
	ds_read_b128 v[72:75], v55 offset:5248
	s_waitcnt lgkmcnt(4)
	ds_read_b128 v[238:241], v55 offset:576
	ds_read_b128 v[242:245], v55 offset:4608
	ds_read_b128 v[246:249], v55 offset:5184
	v_mfma_f32_16x16x32_bf16 v[56:59], v[60:63], v[6:9], v[56:59]
	s_waitcnt lgkmcnt(2)
	v_mfma_f32_16x16x32_bf16 v[60:63], v[238:241], v[2:5], 0
	v_mfma_f32_16x16x32_bf16 v[60:63], v[64:67], v[6:9], v[60:63]
	s_waitcnt lgkmcnt(1)
	v_mfma_f32_16x16x32_bf16 v[64:67], v[242:245], v[2:5], 0
	v_mfma_f32_16x16x32_bf16 v[64:67], v[68:71], v[6:9], v[64:67]
	ds_read_b128 v[210:213], v84 offset:11520
	ds_read_b128 v[214:217], v84 offset:11584
	ds_read_b128 v[218:221], v84 offset:13824
	ds_read_b128 v[222:225], v84 offset:13888
	ds_read_b128 v[226:229], v84 offset:16128
	ds_read_b128 v[230:233], v84 offset:16192
	v_mul_f32_e32 v55, 0x3e38aa3b, v56
	s_waitcnt lgkmcnt(0)
	v_mfma_f32_16x16x32_bf16 v[68:71], v[246:249], v[2:5], 0
	v_mfma_f32_16x16x32_bf16 v[68:71], v[72:75], v[6:9], v[68:71]
	v_mul_f32_e32 v72, 0x3e38aa3b, v57
	v_max3_f32 v55, v55, s88, v72
	v_mul_f32_e32 v72, 0x3e38aa3b, v58
	v_mul_f32_e32 v73, 0x3e38aa3b, v59
	v_max3_f32 v55, v55, v72, v73
	v_mul_f32_e32 v72, 0x3e38aa3b, v60
	v_mul_f32_e32 v73, 0x3e38aa3b, v61
	v_max3_f32 v55, v55, v72, v73
	v_mul_f32_e32 v72, 0x3e38aa3b, v62
	v_mul_f32_e32 v73, 0x3e38aa3b, v63
	v_max3_f32 v55, v55, v72, v73
	v_mul_f32_e32 v72, 0x3e38aa3b, v64
	v_mul_f32_e32 v73, 0x3e38aa3b, v65
	v_max3_f32 v55, v55, v72, v73
	v_mul_f32_e32 v72, 0x3e38aa3b, v66
	v_mul_f32_e32 v73, 0x3e38aa3b, v67
	v_max3_f32 v55, v55, v72, v73
	v_mul_f32_e32 v72, 0x3e38aa3b, v68
	v_mul_f32_e32 v73, 0x3e38aa3b, v69
	v_max3_f32 v55, v55, v72, v73
	v_mul_f32_e32 v72, 0x3e38aa3b, v70
	v_mul_f32_e32 v73, 0x3e38aa3b, v71
	v_max3_f32 v55, v55, v72, v73
	v_mov_b32_e32 v252, v55
	v_mov_b32_e32 v253, v55
	s_nop 1
	v_permlane16_swap_b32_e32 v252, v253
	s_waitcnt lgkmcnt(0)
	v_max_f32_e32 v55, v252, v253
	v_mov_b32_e32 v254, v55
	v_mov_b32_e32 v255, v55
	s_nop 1
	v_permlane32_swap_b32_e32 v254, v255
	s_waitcnt lgkmcnt(0)
	v_max3_f32 v55, v52, v254, v255
	v_sub_f32_e32 v52, v52, v55
	v_fma_f32 v56, v56, s91, -v55
	v_fma_f32 v57, v57, s91, -v55
	v_fma_f32 v58, v58, s91, -v55
	v_fma_f32 v59, v59, s91, -v55
	v_fma_f32 v60, v60, s91, -v55
	v_fma_f32 v61, v61, s91, -v55
	v_fma_f32 v62, v62, s91, -v55
	v_fma_f32 v63, v63, s91, -v55
	v_exp_f32_e32 v52, v52
	v_exp_f32_e32 v56, v56
	v_exp_f32_e32 v57, v57
	v_exp_f32_e32 v58, v58
	v_exp_f32_e32 v59, v59
	v_exp_f32_e32 v60, v60
	v_exp_f32_e32 v61, v61
	v_exp_f32_e32 v62, v62
	v_exp_f32_e32 v63, v63
	v_pk_mul_f32 v[28:29], v[28:29], v[52:53] op_sel_hi:[1,0]
	v_pk_mul_f32 v[26:27], v[26:27], v[52:53] op_sel_hi:[1,0]
	v_cvt_pk_bf16_f32 v72, v56, v57
	v_cvt_pk_bf16_f32 v73, v58, v59
	v_cvt_pk_bf16_f32 v74, v60, v61
	v_cvt_pk_bf16_f32 v75, v62, v63
	v_fma_f32 v64, v64, s91, -v55
	v_fma_f32 v65, v65, s91, -v55
	v_mfma_f32_16x16x32_bf16 v[26:29], v[80:83], v[72:75], v[26:29]
	ds_read_b128 v[80:83], v84 offset:9280
	v_fma_f32 v66, v66, s91, -v55
	v_fma_f32 v67, v67, s91, -v55
	v_fma_f32 v68, v68, s91, -v55
	v_fma_f32 v69, v69, s91, -v55
	v_fma_f32 v70, v70, s91, -v55
	v_fma_f32 v71, v71, s91, -v55
	v_exp_f32_e32 v64, v64
	v_exp_f32_e32 v65, v65
	v_exp_f32_e32 v66, v66
	v_exp_f32_e32 v67, v67
	v_exp_f32_e32 v68, v68
	v_exp_f32_e32 v69, v69
	v_exp_f32_e32 v70, v70
	v_exp_f32_e32 v71, v71
	v_cvt_pk_bf16_f32 v76, v64, v65
	v_cvt_pk_bf16_f32 v77, v66, v67
	v_cvt_pk_bf16_f32 v78, v68, v69
	v_cvt_pk_bf16_f32 v79, v70, v71
	v_pk_mul_f32 v[32:33], v[32:33], v[52:53] op_sel_hi:[1,0]
	v_pk_mul_f32 v[30:31], v[30:31], v[52:53] op_sel_hi:[1,0]
	s_waitcnt lgkmcnt(0)
	v_mfma_f32_16x16x32_bf16 v[26:29], v[80:83], v[76:79], v[26:29]
	v_pk_mul_f32 v[36:37], v[36:37], v[52:53] op_sel_hi:[1,0]
	v_pk_mul_f32 v[34:35], v[34:35], v[52:53] op_sel_hi:[1,0]
	s_waitcnt lgkmcnt(6)
	v_mfma_f32_16x16x32_bf16 v[30:33], v[210:213], v[72:75], v[30:33]
	v_pk_mul_f32 v[40:41], v[40:41], v[52:53] op_sel_hi:[1,0]
	v_pk_mul_f32 v[38:39], v[38:39], v[52:53] op_sel_hi:[1,0]
	s_waitcnt lgkmcnt(5)
	v_mfma_f32_16x16x32_bf16 v[30:33], v[214:217], v[76:79], v[30:33]
	s_waitcnt lgkmcnt(4)
	v_mfma_f32_16x16x32_bf16 v[34:37], v[218:221], v[72:75], v[34:37]
	s_waitcnt lgkmcnt(3)
	v_mfma_f32_16x16x32_bf16 v[34:37], v[222:225], v[76:79], v[34:37]
	s_waitcnt lgkmcnt(2)
	v_mfma_f32_16x16x32_bf16 v[38:41], v[226:229], v[72:75], v[38:41]
	s_waitcnt lgkmcnt(1)
	v_mfma_f32_16x16x32_bf16 v[38:41], v[230:233], v[76:79], v[38:41]
	s_cbranch_vccnz .LBB0_1165
	s_bitcmp1_b32 s12, 0
	s_cselect_b32 s13, 0x4800, 0
	v_add_u32_e32 v72, s13, v46
	s_waitcnt vmcnt(3)
	ds_write_b128 v72, v[14:17]
	s_waitcnt vmcnt(2)
	ds_write_b128 v72, v[10:13] offset:16
	s_waitcnt vmcnt(0)
	ds_write_b128 v72, v[22:25] offset:9216
	ds_write_b128 v72, v[18:21] offset:9232

.LBB0_1184:
	s_cmp_gt_u32 s14, 3
	s_cselect_b64 s[68:69], -1, 0
	s_bitcmp1_b32 s14, 0
	s_cselect_b32 s14, 0x4800, 0
	v_or_b32_e32 v87, s14, v57
	v_add_u32_e32 v76, v87, v55
	ds_read_b128 v[60:63], v76
	ds_read_b128 v[64:67], v76 offset:64
	s_waitcnt vmcnt(1) lgkmcnt(1)
	v_mfma_f32_16x16x32_bf16 v[60:63], v[60:63], v[2:5], 0
	ds_read_b128 v[68:71], v76 offset:640
	ds_read_b128 v[72:75], v76 offset:4672
	s_waitcnt vmcnt(0) lgkmcnt(2)
	ds_read_b128 v[238:241], v76 offset:576
	ds_read_b128 v[242:245], v76 offset:4608
	v_mfma_f32_16x16x32_bf16 v[60:63], v[64:67], v[6:9], v[60:63]
	s_waitcnt lgkmcnt(1)
	v_mfma_f32_16x16x32_bf16 v[64:67], v[238:241], v[2:5], 0
	s_nop 4
	v_mul_f32_e32 v60, 0x3e38aa3b, v60
	v_mfma_f32_16x16x32_bf16 v[64:67], v[68:71], v[6:9], v[64:67]
	s_waitcnt lgkmcnt(0)
	v_mfma_f32_16x16x32_bf16 v[68:71], v[242:245], v[2:5], 0
	v_mfma_f32_16x16x32_bf16 v[68:71], v[72:75], v[6:9], v[68:71]
	ds_read_b128 v[72:75], v76 offset:5184
	ds_read_b128 v[76:79], v76 offset:5248
	s_waitcnt lgkmcnt(1)
	v_mfma_f32_16x16x32_bf16 v[72:75], v[72:75], v[2:5], 0
	s_waitcnt lgkmcnt(0)
	v_mfma_f32_16x16x32_bf16 v[72:75], v[76:79], v[6:9], v[72:75]
	v_add_u32_e32 v76, s12, v58
	v_add_u32_e32 v77, 0xfffffe3f, v76
	v_cmp_gt_u32_e32 vcc, s36, v77
	s_and_b64 vcc, s[68:69], vcc
	s_nop 0
	v_cndmask_b32_e32 v77, v60, v150, vcc
	v_mul_f32_e32 v60, 0x3e38aa3b, v61
	v_add_u32_e32 v61, 0xfffffe40, v76
	v_cmp_gt_u32_e32 vcc, s36, v61
	s_and_b64 vcc, s[68:69], vcc
	v_mul_f32_e32 v61, 0x3e38aa3b, v62
	v_add_u32_e32 v62, 0xfffffe41, v76
	v_cndmask_b32_e32 v78, v60, v150, vcc
	v_cmp_gt_u32_e32 vcc, s36, v62
	s_and_b64 vcc, s[68:69], vcc
	v_add_u32_e32 v62, 0xfffffe42, v76
	v_cndmask_b32_e32 v79, v61, v150, vcc
	v_cmp_gt_u32_e32 vcc, s36, v62
	v_mul_f32_e32 v61, 0x3e38aa3b, v63
	s_and_b64 vcc, s[68:69], vcc
	v_cndmask_b32_e32 v80, v61, v150, vcc
	v_add_u32_e32 v61, 0xfffffe43, v76
	v_cmp_gt_u32_e32 vcc, s36, v61
	v_mul_f32_e32 v62, 0x3e38aa3b, v64
	s_and_b64 vcc, s[68:69], vcc
	v_cndmask_b32_e32 v81, v62, v150, vcc
	v_add_u32_e32 v62, 0xfffffe44, v76
	v_cmp_gt_u32_e32 vcc, s36, v62
	v_mul_f32_e32 v61, 0x3e38aa3b, v65
	s_and_b64 vcc, s[68:69], vcc
	v_add_u32_e32 v62, 0xfffffe45, v76
	v_cndmask_b32_e32 v82, v61, v150, vcc
	v_cmp_gt_u32_e32 vcc, s36, v62
	v_mul_f32_e32 v61, 0x3e38aa3b, v66
	s_and_b64 vcc, s[68:69], vcc
	v_add_u32_e32 v62, 0xfffffe46, v76
	v_cndmask_b32_e32 v83, v61, v150, vcc
	v_cmp_gt_u32_e32 vcc, s36, v62
	v_mul_f32_e32 v61, 0x3e38aa3b, v67
	s_and_b64 vcc, s[68:69], vcc
	v_cndmask_b32_e32 v84, v61, v150, vcc
	v_add_u32_e32 v61, 0xfffffe5f, v76
	v_cmp_gt_u32_e32 vcc, s36, v61
	v_mul_f32_e32 v62, 0x3e38aa3b, v68
	s_and_b64 vcc, s[68:69], vcc
	v_cndmask_b32_e32 v85, v62, v150, vcc
	v_add_u32_e32 v62, 0xfffffe60, v76
	v_cmp_gt_u32_e32 vcc, s36, v62
	v_mul_f32_e32 v61, 0x3e38aa3b, v69
	s_and_b64 vcc, s[68:69], vcc
	v_add_u32_e32 v62, 0xfffffe61, v76
	v_cndmask_b32_e32 v88, v61, v150, vcc
	v_cmp_gt_u32_e32 vcc, s36, v62
	v_mul_f32_e32 v61, 0x3e38aa3b, v70
	s_and_b64 vcc, s[68:69], vcc
	v_add_u32_e32 v62, 0xfffffe62, v76
	v_cndmask_b32_e32 v89, v61, v150, vcc
	v_cmp_gt_u32_e32 vcc, s36, v62
	v_mul_f32_e32 v61, 0x3e38aa3b, v71
	s_and_b64 vcc, s[68:69], vcc
	v_cndmask_b32_e32 v90, v61, v150, vcc
	v_add_u32_e32 v61, 0xfffffe63, v76
	v_cmp_gt_u32_e32 vcc, s36, v61
	v_mul_f32_e32 v62, 0x3e38aa3b, v72
	s_and_b64 vcc, s[68:69], vcc
	v_cndmask_b32_e32 v91, v62, v150, vcc
	v_add_u32_e32 v62, 0xfffffe64, v76
	v_max3_f32 v60, v77, s88, v78
	v_cmp_gt_u32_e32 vcc, s36, v62
	v_max3_f32 v60, v60, v79, v80
	v_mul_f32_e32 v61, 0x3e38aa3b, v73
	s_and_b64 vcc, s[68:69], vcc
	v_add_u32_e32 v62, 0xfffffe65, v76
	v_max3_f32 v60, v60, v81, v82
	v_cndmask_b32_e32 v92, v61, v150, vcc
	v_cmp_gt_u32_e32 vcc, s36, v62
	v_max3_f32 v60, v60, v83, v84
	v_mul_f32_e32 v61, 0x3e38aa3b, v74
	s_and_b64 vcc, s[68:69], vcc
	v_add_u32_e32 v62, 0xfffffe66, v76
	v_max3_f32 v60, v60, v85, v88
	v_cndmask_b32_e32 v93, v61, v150, vcc
	v_cmp_gt_u32_e32 vcc, s36, v62
	v_max3_f32 v60, v60, v89, v90
	v_mul_f32_e32 v61, 0x3e38aa3b, v75
	s_and_b64 vcc, s[68:69], vcc
	v_max3_f32 v60, v60, v91, v92
	v_cndmask_b32_e32 v76, v61, v150, vcc
	v_max3_f32 v60, v60, v93, v76
	v_mov_b32_e32 v252, v60
	v_mov_b32_e32 v253, v60
	s_nop 1
	v_permlane16_swap_b32_e32 v252, v253
	s_andn2_b64 vcc, exec, s[60:61]
	s_waitcnt lgkmcnt(0)
	v_max_f32_e32 v60, v252, v253
	v_mov_b32_e32 v254, v60
	v_mov_b32_e32 v255, v60
	s_nop 1
	v_permlane32_swap_b32_e32 v254, v255
	s_waitcnt lgkmcnt(0)
	v_max3_f32 v60, v52, v254, v255
	v_sub_f32_e32 v61, v77, v60
	v_add_u32_e32 v77, v87, v56
	ds_read_b128 v[210:213], v77 offset:11520
	ds_read_b128 v[214:217], v77 offset:11584
	ds_read_b128 v[218:221], v77 offset:13824
	ds_read_b128 v[222:225], v77 offset:13888
	ds_read_b128 v[226:229], v77 offset:16128
	ds_read_b128 v[230:233], v77 offset:16192
	v_sub_f32_e32 v70, v88, v60
	v_sub_f32_e32 v71, v89, v60
	v_sub_f32_e32 v72, v90, v60
	v_sub_f32_e32 v73, v91, v60
	ds_read_b128 v[88:91], v77 offset:9216
	v_sub_f32_e32 v52, v52, v60
	v_sub_f32_e32 v62, v78, v60
	v_sub_f32_e32 v63, v79, v60
	v_sub_f32_e32 v64, v80, v60
	v_sub_f32_e32 v65, v81, v60
	v_sub_f32_e32 v66, v82, v60
	v_sub_f32_e32 v67, v83, v60
	v_sub_f32_e32 v68, v84, v60
	v_exp_f32_e32 v52, v52
	v_exp_f32_e32 v61, v61
	v_exp_f32_e32 v62, v62
	v_exp_f32_e32 v63, v63
	v_exp_f32_e32 v64, v64
	v_exp_f32_e32 v65, v65
	v_exp_f32_e32 v66, v66
	v_exp_f32_e32 v67, v67
	v_exp_f32_e32 v68, v68
	v_pk_mul_f32 v[28:29], v[28:29], v[52:53] op_sel_hi:[1,0]
	v_pk_mul_f32 v[26:27], v[26:27], v[52:53] op_sel_hi:[1,0]
	v_cvt_pk_bf16_f32 v78, v61, v62
	v_cvt_pk_bf16_f32 v79, v63, v64
	v_cvt_pk_bf16_f32 v80, v65, v66
	v_cvt_pk_bf16_f32 v81, v67, v68
	v_sub_f32_e32 v69, v85, v60
	v_sub_f32_e32 v74, v92, v60
	s_waitcnt lgkmcnt(0)
	v_mfma_f32_16x16x32_bf16 v[26:29], v[88:91], v[78:81], v[26:29]
	ds_read_b128 v[88:91], v77 offset:9280
	v_sub_f32_e32 v75, v93, v60
	v_sub_f32_e32 v76, v76, v60
	v_exp_f32_e32 v69, v69
	v_exp_f32_e32 v70, v70
	v_exp_f32_e32 v71, v71
	v_exp_f32_e32 v72, v72
	v_exp_f32_e32 v73, v73
	v_exp_f32_e32 v74, v74
	v_exp_f32_e32 v75, v75
	v_exp_f32_e32 v76, v76
	v_cvt_pk_bf16_f32 v82, v69, v70
	v_cvt_pk_bf16_f32 v83, v71, v72
	v_cvt_pk_bf16_f32 v84, v73, v74
	v_cvt_pk_bf16_f32 v85, v75, v76
	v_pk_mul_f32 v[32:33], v[32:33], v[52:53] op_sel_hi:[1,0]
	v_pk_mul_f32 v[30:31], v[30:31], v[52:53] op_sel_hi:[1,0]
	s_waitcnt lgkmcnt(0)
	v_mfma_f32_16x16x32_bf16 v[26:29], v[88:91], v[82:85], v[26:29]
	v_pk_mul_f32 v[36:37], v[36:37], v[52:53] op_sel_hi:[1,0]
	v_pk_mul_f32 v[34:35], v[34:35], v[52:53] op_sel_hi:[1,0]
	s_waitcnt lgkmcnt(7)
	v_mfma_f32_16x16x32_bf16 v[30:33], v[210:213], v[78:81], v[30:33]
	v_pk_mul_f32 v[40:41], v[40:41], v[52:53] op_sel_hi:[1,0]
	v_pk_mul_f32 v[38:39], v[38:39], v[52:53] op_sel_hi:[1,0]
	s_waitcnt lgkmcnt(6)
	v_mfma_f32_16x16x32_bf16 v[30:33], v[214:217], v[82:85], v[30:33]
	s_waitcnt lgkmcnt(5)
	v_mfma_f32_16x16x32_bf16 v[34:37], v[218:221], v[78:81], v[34:37]
	s_waitcnt lgkmcnt(4)
	v_mfma_f32_16x16x32_bf16 v[34:37], v[222:225], v[82:85], v[34:37]
	s_waitcnt lgkmcnt(3)
	v_mfma_f32_16x16x32_bf16 v[38:41], v[226:229], v[78:81], v[38:41]
	s_waitcnt lgkmcnt(2)
	v_mfma_f32_16x16x32_bf16 v[38:41], v[230:233], v[82:85], v[38:41]
	s_cbranch_vccnz .LBB0_1186
	s_bitcmp1_b32 s13, 0
	s_cselect_b32 s14, 0x4800, 0
	v_add_u32_e32 v77, s14, v48
	ds_write_b128 v77, v[14:17]
	ds_write_b128 v77, v[10:13] offset:16
	ds_write_b128 v77, v[22:25] offset:9216
	ds_write_b128 v77, v[18:21] offset:9232
